# plus: rwkv_post per-channel parameter loads issued with the streaming loads
# baseline (speedup 1.0000x reference)
.LBB0_963:
	s_lshl_b64 s[40:41], s[6:7], 6
	v_readlane_b32 s2, v252, 37
	s_waitcnt vmcnt(6)
	v_lshlrev_b32_e32 v32, 16, v2
	v_and_b32_e32 v33, 0xffff0000, v2
	v_lshlrev_b32_e32 v24, 16, v3
	v_and_b32_e32 v25, 0xffff0000, v3
	s_add_u32 s40, s2, s40
	v_readlane_b32 s2, v252, 35
	s_addc_u32 s41, s2, s41
	v_lshlrev_b32_e32 v18, 2, v18
	global_load_dword v18, v18, s[40:41]
	v_add_f32_e32 v30, v32, v33
	v_add_f32_e32 v30, v30, v24
	v_add_f32_e32 v30, v30, v25
	s_mov_b32 s2, 0x800000
	s_waitcnt vmcnt(2)
	v_lshlrev_b32_e32 v38, 16, v28
	v_add_f32_dpp v30, v30, v30 quad_perm:[1,0,3,2] row_mask:0xf bank_mask:0xf bound_ctrl:1
	v_and_b32_e32 v39, 0xffff0000, v28
	s_waitcnt vmcnt(1)
	v_lshlrev_b32_e32 v40, 16, v26
	v_add_f32_dpp v30, v30, v30 quad_perm:[2,3,0,1] row_mask:0xf bank_mask:0xf bound_ctrl:1
	v_and_b32_e32 v41, 0xffff0000, v26
	s_lshl_b64 s[6:7], s[6:7], 12
	v_add_f32_dpp v30, v30, v30 row_ror:4 row_mask:0xf bank_mask:0xf bound_ctrl:1
	s_add_u32 s6, s36, s6
	s_addc_u32 s7, s37, s7
	v_add_f32_dpp v30, v30, v30 row_ror:8 row_mask:0xf bank_mask:0xf bound_ctrl:1
	v_fmac_f32_e32 v33, 0xbc800000, v30
	v_fmac_f32_e32 v32, 0xbc800000, v30
	v_fmac_f32_e32 v25, 0xbc800000, v30
	v_fmac_f32_e32 v24, 0xbc800000, v30
	v_pk_mul_f32 v[36:37], v[32:33], v[32:33]
	v_pk_mul_f32 v[34:35], v[24:25], v[24:25]
	v_add_f32_e32 v30, v36, v37
	v_add_f32_e32 v30, v34, v30
	v_add_f32_e32 v30, v35, v30
	v_and_b32_e32 v35, 0xffff0000, v22
	v_lshlrev_b32_e32 v36, 16, v20
	v_add_f32_dpp v30, v30, v30 quad_perm:[1,0,3,2] row_mask:0xf bank_mask:0xf bound_ctrl:1
	v_and_b32_e32 v37, 0xffff0000, v20
	v_pk_add_f32 v[40:41], v[40:41], v[36:37] neg_lo:[0,1] neg_hi:[0,1]
	v_add_f32_dpp v30, v30, v30 quad_perm:[2,3,0,1] row_mask:0xf bank_mask:0xf bound_ctrl:1
	s_add_i32 s25, s25, s4
	s_waitcnt vmcnt(1)
	v_pk_fma_f32 v[48:49], v[48:49], v[40:41], v[36:37]
	v_add_f32_dpp v30, v30, v30 row_ror:4 row_mask:0xf bank_mask:0xf bound_ctrl:1
	v_mul_f32_e32 v20, 0xbfb8aa3b, v48
	v_exp_f32_e32 v20, v20
	v_add_f32_dpp v30, v30, v30 row_ror:8 row_mask:0xf bank_mask:0xf bound_ctrl:1
	v_fmamk_f32 v30, v30, 0x3c800000, v211
	v_cmp_gt_f32_e32 vcc, s2, v30
	v_mul_f32_e32 v34, 0x4b800000, v30
	v_add_f32_e32 v20, 1.0, v20
	v_cndmask_b32_e32 v30, v30, v34, vcc
	v_rsq_f32_e32 v30, v30
	v_rcp_f32_e32 v36, v20
	v_lshlrev_b32_e32 v20, 16, v27
	v_readlane_b32 s2, v250, 58
	v_mul_f32_e32 v34, 0x45800000, v30
	v_cndmask_b32_e32 v30, v30, v34, vcc
	v_lshlrev_b32_e32 v34, 16, v22
	v_pk_mul_f32 v[32:33], v[32:33], v[30:31] op_sel_hi:[1,0]
	s_add_i32 s24, s24, s2
	s_waitcnt vmcnt(1)
	v_pk_fma_f32 v[52:53], v[52:53], v[32:33], v[56:57]
	v_pk_add_f32 v[56:57], v[38:39], v[34:35] neg_lo:[0,1] neg_hi:[0,1]
	s_cmp_lt_i32 s25, 0x10000
	v_pk_fma_f32 v[44:45], v[44:45], v[56:57], v[34:35]
	v_lshlrev_b32_e32 v56, 16, v21
	s_waitcnt vmcnt(0)
	v_pk_fma_f32 v[44:45], v[18:19], v[44:45], v[52:53] op_sel_hi:[0,1,1]
	v_mul_f32_e32 v52, 0xbfb8aa3b, v49
	v_exp_f32_e32 v52, v52
	v_and_b32_e32 v57, 0xffff0000, v21
	v_and_b32_e32 v21, 0xffff0000, v27
	v_pk_add_f32 v[20:21], v[20:21], v[56:57] neg_lo:[0,1] neg_hi:[0,1]
	v_add_f32_e32 v52, 1.0, v52
	v_rcp_f32_e32 v37, v52
	v_pk_fma_f32 v[56:57], v[50:51], v[20:21], v[56:57]
	v_pk_mul_f32 v[20:21], v[24:25], v[30:31] op_sel_hi:[1,0]
	v_mul_f32_e32 v50, 0xbfb8aa3b, v56
	v_pk_mul_f32 v[52:53], v[48:49], v[36:37]
	v_lshlrev_b32_e32 v48, 16, v29
	v_pk_mul_f32 v[44:45], v[52:53], v[44:45]
	v_lshlrev_b32_e32 v52, 16, v23
	v_and_b32_e32 v53, 0xffff0000, v23
	v_and_b32_e32 v49, 0xffff0000, v29
	v_pk_fma_f32 v[54:55], v[54:55], v[20:21], v[58:59]
	v_pk_add_f32 v[58:59], v[48:49], v[52:53] neg_lo:[0,1] neg_hi:[0,1]
	v_exp_f32_e32 v50, v50
	v_pk_fma_f32 v[46:47], v[46:47], v[58:59], v[52:53]
	v_mul_f32_e32 v52, 0xbfb8aa3b, v57
	v_exp_f32_e32 v52, v52
	v_add_f32_e32 v50, 1.0, v50
	v_rcp_f32_e32 v50, v50
	v_pk_fma_f32 v[46:47], v[18:19], v[46:47], v[54:55] op_sel_hi:[0,1,1]
	v_add_f32_e32 v52, 1.0, v52
	v_rcp_f32_e32 v51, v52
	v_cvt_pk_bf16_f32 v44, v44, v45
	v_pk_mul_f32 v[52:53], v[56:57], v[50:51]
	s_nop 0
	v_pk_mul_f32 v[46:47], v[52:53], v[46:47]
	s_nop 0
	v_cvt_pk_bf16_f32 v45, v46, v47
	global_store_dwordx2 v0, v[44:45], s[6:7]
	s_cbranch_scc0 .LBB0_966
.LBB0_964:
	s_ashr_i32 s6, s25, 2
	s_ashr_i32 s7, s6, 31
	s_and_b32 s2, s25, 0x3ffc
	s_lshl_b64 s[40:41], s[6:7], 11
	v_readlane_b32 s5, v251, 63
	s_add_u32 s40, s5, s40
	v_readlane_b32 s5, v252, 36
	v_and_or_b32 v18, s24, 12, v19
	s_addc_u32 s41, s5, s41
	s_mul_i32 s26, s6, 0x3200
	v_lshl_or_b32 v4, v18, 6, v31
	s_mul_hi_i32 s17, s6, 0x3200
	s_add_u32 s42, s22, s26
	s_addc_u32 s43, s23, s17
	v_lshlrev_b32_e32 v0, 1, v4
	v_lshl_add_u64 v[6:7], s[42:43], 0, v[0:1]
	v_add_co_u32_e32 v6, vcc, 0x1000, v6
	global_load_dwordx2 v[2:3], v0, s[40:41]
	s_nop 0
	v_addc_co_u32_e32 v7, vcc, 0, v7, vcc
	global_load_dwordx2 v[22:23], v[6:7], off
	global_load_dwordx2 v[20:21], v[6:7], off offset:2048
	v_lshlrev_b32_e32 v60, 2, v4
	global_load_dwordx4 v[44:47], v60, s[0:1]
	global_load_dwordx4 v[48:51], v60, s[10:11]
	global_load_dwordx4 v[52:55], v60, s[64:65]
	global_load_dwordx4 v[56:59], v60, s[62:63]
	s_cmp_eq_u32 s2, 0
	s_cbranch_scc0 .LBB0_962
	v_mov_b32_e32 v26, 0
	v_mov_b32_e32 v27, 0
	v_mov_b32_e32 v28, 0
	v_mov_b32_e32 v29, 0
	s_branch .LBB0_963
